# v084 with the NA score+bias adds left unpacked (packed f32 beside MFMAs is an anti-lever); keeps one-base bias reads, SALU masks, carried fragment, LN no-invalidate
# baseline (speedup 1.0000x reference)
.Lna_nodma:
	s_cmp_lt_u32 s76, s81
	s_cselect_b64 s[74:75], -1, 0
	s_cmp_gt_u32 s76, s3
	s_cselect_b64 s[76:77], -1, 0
	s_or_b64 s[74:75], s[74:75], s[76:77]
	s_and_b64 vcc, exec, s[74:75]
	s_cbranch_vccnz .LBB0_249
	s_mul_hi_u32 s11, s10, 0x24924925
	s_sub_i32 s74, s10, s11
	s_lshr_b32 s74, s74, 1
	s_add_i32 s74, s74, s11
	s_lshr_b32 s11, s74, 2
	s_mul_i32 s11, s11, 0x1c000
	s_sub_i32 s11, s78, s11
	s_add_i32 s11, s11, 0
	v_add_u32_e32 v130, s11, v158
	v_add_u32_e32 v70, v130, v154
	v_add_u32_e32 v126, v130, v159
	ds_read_b128 v[174:177], v70
	ds_read_b128 v[178:181], v70 offset:4096
	v_add_u32_e32 v131, v130, v160
	ds_read_b128 v[182:185], v126
	ds_read_b128 v[186:189], v126 offset:4096
	v_add_u32_e32 v130, v130, v161
	ds_read_b128 v[190:193], v131
	ds_read_b128 v[194:197], v131 offset:4096
	ds_read_b128 v[198:201], v130
	ds_read_b128 v[202:205], v130 offset:4096
	v_readlane_b32 s76, v252, 32
	v_readlane_b32 s77, v252, 33
	v_add_u32_e32 v165, 0x205f0, v147
	s_mov_b64 s[74:75], -1
	s_and_b64 vcc, exec, s[76:77]
	s_waitcnt lgkmcnt(7)
	v_mfma_f32_32x32x16_bf16 v[82:97], v[174:177], v[98:101], v[32:47]
	s_waitcnt lgkmcnt(6)
	v_mfma_f32_32x32x16_bf16 v[66:81], v[178:181], v[98:101], v[48:63]
	s_waitcnt lgkmcnt(5)
	v_mfma_f32_32x32x16_bf16 v[82:97], v[182:185], v[102:105], v[82:97]
	s_waitcnt lgkmcnt(4)
	v_mfma_f32_32x32x16_bf16 v[66:81], v[186:189], v[102:105], v[66:81]
	s_waitcnt lgkmcnt(3)
	v_mfma_f32_32x32x16_bf16 v[82:97], v[190:193], v[106:109], v[82:97]
	s_waitcnt lgkmcnt(2)
	v_mfma_f32_32x32x16_bf16 v[66:81], v[194:197], v[106:109], v[66:81]
	s_waitcnt lgkmcnt(1)
	v_mfma_f32_32x32x16_bf16 v[82:97], v[198:201], v[110:113], v[82:97]
	s_waitcnt lgkmcnt(0)
	v_mfma_f32_32x32x16_bf16 v[66:81], v[202:205], v[110:113], v[66:81]
	s_cbranch_vccz .LBB0_238
	ds_read2_b32 v[122:123], v165 offset0:40 offset1:41
	ds_read2_b32 v[124:125], v165 offset0:42 offset1:43
	ds_read2_b32 v[126:127], v165 offset0:48 offset1:49
	ds_read2_b32 v[128:129], v165 offset0:50 offset1:51
	ds_read2_b32 v[130:131], v165 offset0:32 offset1:33
	ds_read2_b32 v[132:133], v165 offset0:56 offset1:57
	ds_read2_b32 v[134:135], v165 offset0:34 offset1:35
	ds_read2_b32 v[136:137], v165 offset0:58 offset1:59
	ds_read2_b32 v[170:171], v165 offset0:24 offset1:25
	ds_read2_b32 v[172:173], v165 offset0:26 offset1:27
	s_mov_b64 s[74:75], 0
	s_waitcnt lgkmcnt(1)
	v_mov_b32_e32 v163, v170
	s_waitcnt lgkmcnt(0)
	v_mov_b32_e32 v169, v172
	s_nop 0
	v_add_f32_e32 v130, v66, v130
	v_exp_f32_e32 v130, v130
	v_add_f32_e32 v131, v67, v131
	v_exp_f32_e32 v131, v131
	v_add_f32_e32 v134, v68, v134
	v_exp_f32_e32 v134, v134
	v_add_f32_e32 v135, v69, v135
	v_exp_f32_e32 v135, v135
	v_add_f32_e32 v70, v70, v122
	v_exp_f32_e32 v70, v70
	v_add_f32_e32 v71, v71, v123
	v_add_f32_e32 v170, v131, v130
	v_exp_f32_e32 v71, v71
	v_add_f32_e32 v72, v72, v124
	v_add_f32_e32 v170, v134, v170
	v_exp_f32_e32 v72, v72
	v_add_f32_e32 v73, v73, v125
	v_add_f32_e32 v170, v135, v170
	v_exp_f32_e32 v73, v73
	v_add_f32_e32 v74, v74, v126
	v_add_f32_e32 v122, v70, v170
	v_exp_f32_e32 v74, v74
	v_add_f32_e32 v75, v75, v127
	v_add_f32_e32 v122, v71, v122
	v_exp_f32_e32 v75, v75
	v_add_f32_e32 v76, v76, v128
	v_add_f32_e32 v122, v72, v122
	v_exp_f32_e32 v76, v76
	v_add_f32_e32 v77, v77, v129
	v_add_f32_e32 v122, v73, v122
	v_exp_f32_e32 v77, v77
	v_add_f32_e32 v78, v78, v132
	v_add_f32_e32 v122, v74, v122
	v_exp_f32_e32 v78, v78
	v_add_f32_e32 v79, v79, v133
	v_add_f32_e32 v122, v75, v122
	v_exp_f32_e32 v79, v79
	v_add_f32_e32 v80, v80, v136
	v_add_f32_e32 v122, v76, v122
	v_exp_f32_e32 v80, v80
	v_add_f32_e32 v81, v81, v137
	v_add_f32_e32 v122, v77, v122
	v_exp_f32_e32 v81, v81
	v_add_f32_e32 v123, v94, v163
	v_add_f32_e32 v122, v78, v122
	v_exp_f32_e32 v123, v123
	v_add_f32_e32 v124, v95, v171
	v_add_f32_e32 v122, v79, v122
	v_exp_f32_e32 v124, v124
	v_add_f32_e32 v125, v96, v169
	v_add_f32_e32 v126, v97, v173
	v_add_f32_e32 v122, v80, v122
	v_exp_f32_e32 v125, v125
	v_exp_f32_e32 v126, v126
	v_add_f32_e32 v122, v81, v122
	v_add_f32_e32 v122, v123, v122
	v_add_f32_e32 v122, v124, v122
	v_add_f32_e32 v122, v125, v122
	v_cvt_pk_bf16_f32 v132, v123, v124
	v_cvt_pk_bf16_f32 v133, v125, v126
	v_cvt_pk_bf16_f32 v120, v78, v79
	v_cvt_pk_bf16_f32 v121, v80, v81
	v_add_f32_e32 v163, v126, v122
	v_cvt_pk_bf16_f32 v127, v134, v135
	v_cvt_pk_bf16_f32 v118, v74, v75
	v_cvt_pk_bf16_f32 v119, v76, v77
	v_mov_b64_e32 v[136:137], v[120:121]
	v_cvt_pk_bf16_f32 v126, v130, v131
	v_cvt_pk_bf16_f32 v128, v70, v71
	v_cvt_pk_bf16_f32 v129, v72, v73
	v_mov_b64_e32 v[134:135], v[118:119]
.LBB0_238:
	v_mov_b32_e32 v130, 0
	s_andn2_b64 vcc, exec, s[74:75]
	v_mov_b32_e32 v131, v130
	s_cbranch_vccnz .LBB0_240
	s_nop 6
	ds_read2_b32 v[114:115], v165 offset0:26 offset1:27
	ds_read2_b32 v[116:117], v165 offset0:18 offset1:19
	ds_read2_b32 v[122:123], v165 offset0:32 offset1:33
	ds_read2_b32 v[124:125], v165 offset0:34 offset1:35
	ds_read2_b32 v[70:71], v165 offset1:1
	ds_read2_b32 v[72:73], v165 offset0:2 offset1:3
	ds_read2_b32 v[74:75], v165 offset0:8 offset1:9
	ds_read2_b32 v[76:77], v165 offset0:10 offset1:11
	ds_read2_b32 v[78:79], v165 offset0:16 offset1:17
	ds_read2_b32 v[80:81], v165 offset0:24 offset1:25
	s_waitcnt lgkmcnt(0)
	s_nop 0
	v_add_f32_e32 v70, v82, v70
	v_exp_f32_e32 v70, v70
	v_add_f32_e32 v71, v83, v71
	v_exp_f32_e32 v71, v71
	v_add_f32_e32 v72, v84, v72
	v_exp_f32_e32 v72, v72
	v_add_f32_e32 v73, v85, v73
	v_exp_f32_e32 v73, v73
	v_add_f32_e32 v74, v86, v74
	v_exp_f32_e32 v74, v74
	v_add_f32_e32 v75, v87, v75
	v_add_f32_e32 v82, v71, v70
	v_exp_f32_e32 v75, v75
	v_add_f32_e32 v76, v88, v76
	v_add_f32_e32 v82, v72, v82
	v_exp_f32_e32 v76, v76
	v_add_f32_e32 v77, v89, v77
	v_add_f32_e32 v82, v73, v82
	v_exp_f32_e32 v77, v77
	v_add_f32_e32 v78, v90, v78
	v_add_f32_e32 v82, v74, v82
	v_exp_f32_e32 v78, v78
	v_add_f32_e32 v79, v91, v79
	v_add_f32_e32 v82, v75, v82
	v_exp_f32_e32 v79, v79
	v_add_f32_e32 v83, v92, v116
	v_add_f32_e32 v82, v76, v82
	v_exp_f32_e32 v83, v83
	v_add_f32_e32 v84, v93, v117
	v_add_f32_e32 v82, v77, v82
	v_exp_f32_e32 v84, v84
	v_add_f32_e32 v80, v94, v80
	v_add_f32_e32 v82, v78, v82
	v_exp_f32_e32 v80, v80
	v_add_f32_e32 v81, v95, v81
	v_add_f32_e32 v82, v79, v82
	v_exp_f32_e32 v81, v81
	v_add_f32_e32 v85, v96, v114
	v_add_f32_e32 v82, v83, v82
	v_exp_f32_e32 v85, v85
	v_add_f32_e32 v86, v97, v115
	v_add_f32_e32 v82, v84, v82
	v_exp_f32_e32 v86, v86
	v_add_f32_e32 v66, v66, v122
	v_add_f32_e32 v82, v80, v82
	v_exp_f32_e32 v66, v66
	v_add_f32_e32 v67, v67, v123
	v_add_f32_e32 v82, v81, v82
	v_exp_f32_e32 v67, v67
	v_add_f32_e32 v68, v68, v124
	v_add_f32_e32 v82, v85, v82
	v_exp_f32_e32 v68, v68
	v_add_f32_e32 v69, v69, v125
	v_add_f32_e32 v82, v86, v82
	v_exp_f32_e32 v69, v69
	v_add_f32_e32 v82, v66, v82
	v_add_f32_e32 v82, v67, v82
	v_add_f32_e32 v82, v68, v82
	v_mov_b64_e32 v[136:137], v[120:121]
	v_add_f32_e32 v163, v69, v82
	v_cvt_pk_bf16_f32 v114, v70, v71
	v_cvt_pk_bf16_f32 v115, v72, v73
	v_cvt_pk_bf16_f32 v116, v74, v75
	v_cvt_pk_bf16_f32 v117, v76, v77
	v_cvt_pk_bf16_f32 v130, v78, v79
	v_cvt_pk_bf16_f32 v131, v83, v84
	v_cvt_pk_bf16_f32 v132, v80, v81
	v_cvt_pk_bf16_f32 v133, v85, v86
	v_cvt_pk_bf16_f32 v126, v66, v67
	v_cvt_pk_bf16_f32 v127, v68, v69
	v_mov_b32_e32 v128, 0
	v_mov_b64_e32 v[134:135], v[118:119]
	v_mov_b32_e32 v129, 0
